# P9 + P11 epilogues: residual / sumsq / norm-weight loads hoisted and issued up front, counted vmcnt waits, stores unwaited
# baseline (speedup 1.0000x reference)
.LBB0_1449:
	ds_read_b128 v[140:143], v167
	ds_read_b128 v[144:147], v167 offset:1024
	ds_read_b128 v[148:151], v167 offset:2048
	ds_read_b128 v[152:155], v167 offset:3072
	ds_read_b128 v[156:159], v168
	ds_read_b128 v[172:175], v168 offset:1024
	ds_read_b128 v[176:179], v168 offset:2048
	ds_read_b128 v[180:183], v168 offset:3072
	s_add_u32 s20, s0, 0xffea0080
	s_addc_u32 s21, s1, -1
	s_cmpk_eq_i32 s52, 0x54
	s_cselect_b32 s23, s25, s21
	s_cselect_b32 s22, s47, s20
	s_cselect_b32 s21, s48, s51
	s_cselect_b32 s20, s49, s50
	v_lshl_add_u64 v[160:161], s[0:1], 0, v[136:137]
	s_add_i32 m0, s29, 0xc000
	ds_read_b128 v[184:187], v169
	ds_read_b128 v[188:191], v169 offset:1024
	ds_read_b128 v[192:195], v169 offset:2048
	ds_read_b128 v[196:199], v169 offset:3072
	ds_read_b128 v[200:203], v169 offset:4096
	ds_read_b128 v[204:207], v169 offset:5120
	ds_read_b128 v[208:211], v169 offset:6144
	ds_read_b128 v[212:215], v169 offset:7168
	global_load_lds_dwordx4 v[160:161], off
	v_lshl_add_u64 v[160:161], s[0:1], 0, v[138:139]
	s_add_i32 m0, s29, 0xe000
	s_nop 0
	global_load_lds_dwordx4 v[160:161], off
	s_waitcnt vmcnt(8)
	s_waitcnt lgkmcnt(0)
	s_barrier
	s_setprio 1
	s_waitcnt lgkmcnt(0)
	v_mfma_f32_16x16x32_bf16 v[124:127], v[140:143], v[184:187], v[124:127]
	v_mfma_f32_16x16x32_bf16 v[120:123], v[148:151], v[184:187], v[120:123]
	v_mfma_f32_16x16x32_bf16 v[108:111], v[140:143], v[192:195], v[108:111]
	v_mfma_f32_16x16x32_bf16 v[104:107], v[148:151], v[192:195], v[104:107]
	v_mfma_f32_16x16x32_bf16 v[92:95], v[140:143], v[200:203], v[92:95]
	v_mfma_f32_16x16x32_bf16 v[88:91], v[148:151], v[200:203], v[88:91]
	v_mfma_f32_16x16x32_bf16 v[76:79], v[140:143], v[208:211], v[76:79]
	v_mfma_f32_16x16x32_bf16 v[72:75], v[148:151], v[208:211], v[72:75]
	v_mfma_f32_16x16x32_bf16 v[124:127], v[144:147], v[188:191], v[124:127]
	v_mfma_f32_16x16x32_bf16 v[120:123], v[152:155], v[188:191], v[120:123]
	v_mfma_f32_16x16x32_bf16 v[108:111], v[144:147], v[196:199], v[108:111]
	v_mfma_f32_16x16x32_bf16 v[104:107], v[152:155], v[196:199], v[104:107]
	v_mfma_f32_16x16x32_bf16 v[92:95], v[144:147], v[204:207], v[92:95]
	v_mfma_f32_16x16x32_bf16 v[88:91], v[152:155], v[204:207], v[88:91]
	v_mfma_f32_16x16x32_bf16 v[76:79], v[144:147], v[212:215], v[76:79]
	v_mfma_f32_16x16x32_bf16 v[72:75], v[152:155], v[212:215], v[72:75]
	s_setprio 0
	s_setprio 1
	v_mfma_f32_16x16x32_bf16 v[116:119], v[156:159], v[184:187], v[116:119]
	v_mfma_f32_16x16x32_bf16 v[112:115], v[176:179], v[184:187], v[112:115]
	v_mfma_f32_16x16x32_bf16 v[100:103], v[156:159], v[192:195], v[100:103]
	v_mfma_f32_16x16x32_bf16 v[96:99], v[176:179], v[192:195], v[96:99]
	v_mfma_f32_16x16x32_bf16 v[84:87], v[156:159], v[200:203], v[84:87]
	v_mfma_f32_16x16x32_bf16 v[80:83], v[176:179], v[200:203], v[80:83]
	v_mfma_f32_16x16x32_bf16 v[68:71], v[156:159], v[208:211], v[68:71]
	v_mfma_f32_16x16x32_bf16 v[64:67], v[176:179], v[208:211], v[64:67]
	v_mfma_f32_16x16x32_bf16 v[116:119], v[172:175], v[188:191], v[116:119]
	v_mfma_f32_16x16x32_bf16 v[112:115], v[180:183], v[188:191], v[112:115]
	v_mfma_f32_16x16x32_bf16 v[100:103], v[172:175], v[196:199], v[100:103]
	v_mfma_f32_16x16x32_bf16 v[96:99], v[180:183], v[196:199], v[96:99]
	v_mfma_f32_16x16x32_bf16 v[84:87], v[172:175], v[204:207], v[84:87]
	v_mfma_f32_16x16x32_bf16 v[80:83], v[180:183], v[204:207], v[80:83]
	v_mfma_f32_16x16x32_bf16 v[68:71], v[172:175], v[212:215], v[68:71]
	v_mfma_f32_16x16x32_bf16 v[64:67], v[180:183], v[212:215], v[64:67]
	s_setprio 0
	s_barrier
	s_add_i32 s53, s42, s28
	v_lshl_add_u64 v[160:161], s[20:21], 0, v[130:131]
	s_mov_b32 m0, s53
	ds_read_b128 v[184:187], v169 offset:16384
	ds_read_b128 v[188:191], v169 offset:17408
	ds_read_b128 v[192:195], v169 offset:18432
	ds_read_b128 v[196:199], v169 offset:19456
	ds_read_b128 v[200:203], v169 offset:20480
	ds_read_b128 v[204:207], v169 offset:21504
	ds_read_b128 v[208:211], v169 offset:22528
	ds_read_b128 v[212:215], v169 offset:23552
	global_load_lds_dwordx4 v[160:161], off
	s_add_i32 m0, s53, 0x2000
	s_add_u32 s54, s20, 0x160000
	v_lshl_add_u64 v[216:217], s[20:21], 0, v[134:135]
	s_addc_u32 s55, s21, 0
	s_add_i32 s53, s43, s28
	global_load_lds_dwordx4 v[216:217], off
	v_lshl_add_u64 v[218:219], s[54:55], 0, v[130:131]
	s_mov_b32 m0, s53
	v_lshl_add_u64 v[220:221], s[22:23], 0, v[132:133]
	global_load_lds_dwordx4 v[218:219], off
	v_lshl_add_u64 v[218:219], s[54:55], 0, v[134:135]
	s_add_i32 m0, s53, 0x2000
	s_nop 0
	global_load_lds_dwordx4 v[218:219], off
	v_lshl_add_u64 v[218:219], s[22:23], 0, v[128:129]
	s_mov_b32 m0, s29
	s_nop 0
	global_load_lds_dwordx4 v[218:219], off
	s_mov_b32 m0, s30
	s_nop 0
	global_load_lds_dwordx4 v[220:221], off
	s_waitcnt vmcnt(8)
	s_waitcnt lgkmcnt(0)
	s_barrier
	s_setprio 1
	s_waitcnt lgkmcnt(0)
	v_mfma_f32_16x16x32_bf16 v[60:63], v[140:143], v[184:187], v[60:63]
	v_mfma_f32_16x16x32_bf16 v[56:59], v[148:151], v[184:187], v[56:59]
	v_mfma_f32_16x16x32_bf16 v[44:47], v[140:143], v[192:195], v[44:47]
	v_mfma_f32_16x16x32_bf16 v[40:43], v[148:151], v[192:195], v[40:43]
	v_mfma_f32_16x16x32_bf16 v[28:31], v[140:143], v[200:203], v[28:31]
	v_mfma_f32_16x16x32_bf16 v[24:27], v[148:151], v[200:203], v[24:27]
	v_mfma_f32_16x16x32_bf16 v[12:15], v[140:143], v[208:211], v[12:15]
	v_mfma_f32_16x16x32_bf16 v[8:11], v[148:151], v[208:211], v[8:11]
	v_mfma_f32_16x16x32_bf16 v[60:63], v[144:147], v[188:191], v[60:63]
	v_mfma_f32_16x16x32_bf16 v[56:59], v[152:155], v[188:191], v[56:59]
	v_mfma_f32_16x16x32_bf16 v[44:47], v[144:147], v[196:199], v[44:47]
	v_mfma_f32_16x16x32_bf16 v[40:43], v[152:155], v[196:199], v[40:43]
	v_mfma_f32_16x16x32_bf16 v[28:31], v[144:147], v[204:207], v[28:31]
	v_mfma_f32_16x16x32_bf16 v[24:27], v[152:155], v[204:207], v[24:27]
	v_mfma_f32_16x16x32_bf16 v[12:15], v[144:147], v[212:215], v[12:15]
	v_mfma_f32_16x16x32_bf16 v[8:11], v[152:155], v[212:215], v[8:11]
	s_setprio 0
	s_setprio 1
	v_mfma_f32_16x16x32_bf16 v[52:55], v[156:159], v[184:187], v[52:55]
	v_mfma_f32_16x16x32_bf16 v[48:51], v[176:179], v[184:187], v[48:51]
	v_mfma_f32_16x16x32_bf16 v[36:39], v[156:159], v[192:195], v[36:39]
	v_mfma_f32_16x16x32_bf16 v[32:35], v[176:179], v[192:195], v[32:35]
	v_mfma_f32_16x16x32_bf16 v[20:23], v[156:159], v[200:203], v[20:23]
	v_mfma_f32_16x16x32_bf16 v[16:19], v[176:179], v[200:203], v[16:19]
	v_mfma_f32_16x16x32_bf16 v[4:7], v[156:159], v[208:211], v[4:7]
	v_mfma_f32_16x16x32_bf16 v[0:3], v[176:179], v[208:211], v[0:3]
	v_mfma_f32_16x16x32_bf16 v[52:55], v[172:175], v[188:191], v[52:55]
	v_mfma_f32_16x16x32_bf16 v[48:51], v[180:183], v[188:191], v[48:51]
	v_mfma_f32_16x16x32_bf16 v[36:39], v[172:175], v[196:199], v[36:39]
	v_mfma_f32_16x16x32_bf16 v[32:35], v[180:183], v[196:199], v[32:35]
	v_mfma_f32_16x16x32_bf16 v[20:23], v[172:175], v[204:207], v[20:23]
	v_mfma_f32_16x16x32_bf16 v[16:19], v[180:183], v[204:207], v[16:19]
	v_mfma_f32_16x16x32_bf16 v[4:7], v[172:175], v[212:215], v[4:7]
	v_mfma_f32_16x16x32_bf16 v[0:3], v[180:183], v[212:215], v[0:3]
	s_setprio 0
	s_barrier
	s_add_i32 s53, 0, 0x18000
	s_add_i32 s54, 0, 0x1c000
	v_add_u32_e32 v152, s53, v166
	v_add_u32_e32 v180, s54, v166
	ds_read_b128 v[140:143], v152
	ds_read_b128 v[144:147], v152 offset:1024
	ds_read_b128 v[148:151], v152 offset:2048
	ds_read_b128 v[152:155], v152 offset:3072
	ds_read_b128 v[156:159], v180
	ds_read_b128 v[172:175], v180 offset:1024
	ds_read_b128 v[176:179], v180 offset:2048
	ds_read_b128 v[180:183], v180 offset:3072
	s_add_u32 s22, s22, 0x160000
	s_addc_u32 s23, s23, 0
	s_mov_b32 m0, s31
	v_lshl_add_u64 v[222:223], s[22:23], 0, v[128:129]
	ds_read_b128 v[184:187], v169 offset:32768
	ds_read_b128 v[188:191], v169 offset:33792
	ds_read_b128 v[192:195], v169 offset:34816
	ds_read_b128 v[196:199], v169 offset:35840
	ds_read_b128 v[200:203], v169 offset:36864
	ds_read_b128 v[204:207], v169 offset:37888
	ds_read_b128 v[208:211], v169 offset:38912
	ds_read_b128 v[212:215], v169 offset:39936
	global_load_lds_dwordx4 v[222:223], off
	v_lshl_add_u64 v[222:223], s[22:23], 0, v[132:133]
	s_mov_b32 m0, s33
	s_nop 0
	global_load_lds_dwordx4 v[222:223], off
	s_waitcnt vmcnt(8)
	s_waitcnt lgkmcnt(0)
	s_barrier
	s_setprio 1
	s_waitcnt lgkmcnt(0)
	v_mfma_f32_16x16x32_bf16 v[124:127], v[140:143], v[184:187], v[124:127]
	v_mfma_f32_16x16x32_bf16 v[120:123], v[148:151], v[184:187], v[120:123]
	v_mfma_f32_16x16x32_bf16 v[108:111], v[140:143], v[192:195], v[108:111]
	v_mfma_f32_16x16x32_bf16 v[104:107], v[148:151], v[192:195], v[104:107]
	v_mfma_f32_16x16x32_bf16 v[92:95], v[140:143], v[200:203], v[92:95]
	v_mfma_f32_16x16x32_bf16 v[88:91], v[148:151], v[200:203], v[88:91]
	v_mfma_f32_16x16x32_bf16 v[76:79], v[140:143], v[208:211], v[76:79]
	v_mfma_f32_16x16x32_bf16 v[72:75], v[148:151], v[208:211], v[72:75]
	v_mfma_f32_16x16x32_bf16 v[124:127], v[144:147], v[188:191], v[124:127]
	v_mfma_f32_16x16x32_bf16 v[120:123], v[152:155], v[188:191], v[120:123]
	v_mfma_f32_16x16x32_bf16 v[108:111], v[144:147], v[196:199], v[108:111]
	v_mfma_f32_16x16x32_bf16 v[104:107], v[152:155], v[196:199], v[104:107]
	v_mfma_f32_16x16x32_bf16 v[92:95], v[144:147], v[204:207], v[92:95]
	v_mfma_f32_16x16x32_bf16 v[88:91], v[152:155], v[204:207], v[88:91]
	v_mfma_f32_16x16x32_bf16 v[76:79], v[144:147], v[212:215], v[76:79]
	v_mfma_f32_16x16x32_bf16 v[72:75], v[152:155], v[212:215], v[72:75]
	s_setprio 0
	s_setprio 1
	v_mfma_f32_16x16x32_bf16 v[116:119], v[156:159], v[184:187], v[116:119]
	v_mfma_f32_16x16x32_bf16 v[112:115], v[176:179], v[184:187], v[112:115]
	v_mfma_f32_16x16x32_bf16 v[100:103], v[156:159], v[192:195], v[100:103]
	v_mfma_f32_16x16x32_bf16 v[96:99], v[176:179], v[192:195], v[96:99]
	v_mfma_f32_16x16x32_bf16 v[84:87], v[156:159], v[200:203], v[84:87]
	v_mfma_f32_16x16x32_bf16 v[80:83], v[176:179], v[200:203], v[80:83]
	v_mfma_f32_16x16x32_bf16 v[68:71], v[156:159], v[208:211], v[68:71]
	v_mfma_f32_16x16x32_bf16 v[64:67], v[176:179], v[208:211], v[64:67]
	v_mfma_f32_16x16x32_bf16 v[116:119], v[172:175], v[188:191], v[116:119]
	v_mfma_f32_16x16x32_bf16 v[112:115], v[180:183], v[188:191], v[112:115]
	v_mfma_f32_16x16x32_bf16 v[100:103], v[172:175], v[196:199], v[100:103]
	v_mfma_f32_16x16x32_bf16 v[96:99], v[180:183], v[196:199], v[96:99]
	v_mfma_f32_16x16x32_bf16 v[84:87], v[172:175], v[204:207], v[84:87]
	v_mfma_f32_16x16x32_bf16 v[80:83], v[180:183], v[204:207], v[80:83]
	v_mfma_f32_16x16x32_bf16 v[68:71], v[172:175], v[212:215], v[68:71]
	v_mfma_f32_16x16x32_bf16 v[64:67], v[180:183], v[212:215], v[64:67]
	s_setprio 0
	s_barrier
	s_add_i32 s22, s53, s28
	v_lshl_add_u64 v[160:161], v[160:161], 0, s[8:9]
	s_mov_b32 m0, s22
	ds_read_b128 v[184:187], v169 offset:49152
	ds_read_b128 v[188:191], v169 offset:50176
	ds_read_b128 v[192:195], v169 offset:51200
	ds_read_b128 v[196:199], v169 offset:52224
	ds_read_b128 v[200:203], v169 offset:53248
	ds_read_b128 v[204:207], v169 offset:54272
	ds_read_b128 v[208:211], v169 offset:55296
	ds_read_b128 v[212:215], v169 offset:56320
	global_load_lds_dwordx4 v[160:161], off
	s_add_i32 m0, s22, 0x2000
	s_add_u32 s20, s20, 0x160080
	v_lshl_add_u64 v[160:161], v[216:217], 0, s[8:9]
	s_addc_u32 s21, s21, 0
	s_add_i32 s22, s54, s28
	global_load_lds_dwordx4 v[160:161], off
	v_lshl_add_u64 v[160:161], s[20:21], 0, v[130:131]
	s_mov_b32 m0, s22
	s_nop 0
	global_load_lds_dwordx4 v[160:161], off
	v_lshl_add_u64 v[160:161], s[20:21], 0, v[134:135]
	s_add_i32 m0, s22, 0x2000
	s_nop 0
	global_load_lds_dwordx4 v[160:161], off
	v_lshl_add_u64 v[160:161], v[218:219], 0, s[8:9]
	s_mov_b32 m0, s39
	s_nop 0
	global_load_lds_dwordx4 v[160:161], off
	v_lshl_add_u64 v[160:161], v[220:221], 0, s[8:9]
	s_mov_b32 m0, s40
	s_nop 0
	global_load_lds_dwordx4 v[160:161], off
	s_waitcnt vmcnt(8)
	s_waitcnt lgkmcnt(0)
	s_barrier
	s_setprio 1
	s_waitcnt lgkmcnt(0)
	v_mfma_f32_16x16x32_bf16 v[60:63], v[140:143], v[184:187], v[60:63]
	v_mfma_f32_16x16x32_bf16 v[56:59], v[148:151], v[184:187], v[56:59]
	v_mfma_f32_16x16x32_bf16 v[44:47], v[140:143], v[192:195], v[44:47]
	v_mfma_f32_16x16x32_bf16 v[40:43], v[148:151], v[192:195], v[40:43]
	v_mfma_f32_16x16x32_bf16 v[28:31], v[140:143], v[200:203], v[28:31]
	v_mfma_f32_16x16x32_bf16 v[24:27], v[148:151], v[200:203], v[24:27]
	v_mfma_f32_16x16x32_bf16 v[12:15], v[140:143], v[208:211], v[12:15]
	v_mfma_f32_16x16x32_bf16 v[8:11], v[148:151], v[208:211], v[8:11]
	v_mfma_f32_16x16x32_bf16 v[60:63], v[144:147], v[188:191], v[60:63]
	v_mfma_f32_16x16x32_bf16 v[56:59], v[152:155], v[188:191], v[56:59]
	v_mfma_f32_16x16x32_bf16 v[44:47], v[144:147], v[196:199], v[44:47]
	v_mfma_f32_16x16x32_bf16 v[40:43], v[152:155], v[196:199], v[40:43]
	v_mfma_f32_16x16x32_bf16 v[28:31], v[144:147], v[204:207], v[28:31]
	v_mfma_f32_16x16x32_bf16 v[24:27], v[152:155], v[204:207], v[24:27]
	v_mfma_f32_16x16x32_bf16 v[12:15], v[144:147], v[212:215], v[12:15]
	v_mfma_f32_16x16x32_bf16 v[8:11], v[152:155], v[212:215], v[8:11]
	s_setprio 0
	s_setprio 1
	v_mfma_f32_16x16x32_bf16 v[52:55], v[156:159], v[184:187], v[52:55]
	v_mfma_f32_16x16x32_bf16 v[48:51], v[176:179], v[184:187], v[48:51]
	v_mfma_f32_16x16x32_bf16 v[36:39], v[156:159], v[192:195], v[36:39]
	v_mfma_f32_16x16x32_bf16 v[32:35], v[176:179], v[192:195], v[32:35]
	v_mfma_f32_16x16x32_bf16 v[20:23], v[156:159], v[200:203], v[20:23]
	v_mfma_f32_16x16x32_bf16 v[16:19], v[176:179], v[200:203], v[16:19]
	v_mfma_f32_16x16x32_bf16 v[4:7], v[156:159], v[208:211], v[4:7]
	v_mfma_f32_16x16x32_bf16 v[0:3], v[176:179], v[208:211], v[0:3]
	v_mfma_f32_16x16x32_bf16 v[52:55], v[172:175], v[188:191], v[52:55]
	v_mfma_f32_16x16x32_bf16 v[48:51], v[180:183], v[188:191], v[48:51]
	v_mfma_f32_16x16x32_bf16 v[36:39], v[172:175], v[196:199], v[36:39]
	v_mfma_f32_16x16x32_bf16 v[32:35], v[180:183], v[196:199], v[32:35]
	v_mfma_f32_16x16x32_bf16 v[20:23], v[172:175], v[204:207], v[20:23]
	v_mfma_f32_16x16x32_bf16 v[16:19], v[180:183], v[204:207], v[16:19]
	v_mfma_f32_16x16x32_bf16 v[4:7], v[172:175], v[212:215], v[4:7]
	v_mfma_f32_16x16x32_bf16 v[0:3], v[180:183], v[212:215], v[0:3]
	s_setprio 0
	s_barrier
	s_add_i32 s52, s52, 2
	s_add_u32 s0, s0, 0x100
	s_addc_u32 s1, s1, 0
	s_add_u32 s50, s50, 0x100
	s_addc_u32 s51, s51, 0
	s_cmpk_gt_u32 s52, 0x55
	s_cbranch_scc0 .LBB0_1449
	s_lshl_b32 s98, s2, 8
	s_add_i32 s98, s98, s35
	v_add_u32_e32 v254, s98, v163
	s_lshl_b32 s98, s24, 8
	s_or_b32 s98, s98, s36
	v_lshl_add_u32 v255, v164, 3, s98
	v_lshlrev_b32_e32 v254, 12, v254
	v_lshl_add_u32 v254, v255, 1, v254
	v_add_u32_e32 v255, 0xb0000, v254
	global_load_dwordx4 v[190:193], v254, s[62:63]
	global_load_dwordx4 v[194:197], v254, s[62:63] offset:256
	v_add_u32_e32 v254, 0x10000, v254
	global_load_dwordx4 v[198:201], v254, s[62:63]
	global_load_dwordx4 v[202:205], v254, s[62:63] offset:256
	v_add_u32_e32 v254, 0x10000, v254
	global_load_dwordx4 v[206:209], v254, s[62:63]
	global_load_dwordx4 v[210:213], v254, s[62:63] offset:256
	v_add_u32_e32 v254, 0x10000, v254
	global_load_dwordx4 v[214:217], v254, s[62:63]
	global_load_dwordx4 v[218:221], v254, s[62:63] offset:256
	v_add_u32_e32 v254, 0x50000, v254
	global_load_dwordx4 v[222:225], v254, s[62:63]
	global_load_dwordx4 v[230:233], v254, s[62:63] offset:256
	v_add_u32_e32 v254, 0x10000, v254
	global_load_dwordx4 v[234:237], v254, s[62:63]
	global_load_dwordx4 v[238:241], v254, s[62:63] offset:256
	v_add_u32_e32 v254, 0x10000, v254
	global_load_dwordx4 v[242:245], v254, s[62:63]
	global_load_dwordx4 v[246:249], v254, s[62:63] offset:256
	v_add_u32_e32 v254, 0x10000, v254
	global_load_dwordx4 v[250:253], v254, s[62:63]
	s_and_b64 vcc, exec, s[10:11]
	s_cbranch_vccz .LBB0_1452
	s_barrier
.LBB0_1452:
	v_mov_b32_e32 v140, v165
	v_mov_b32_e32 v160, v163
	v_mov_b32_e32 v141, v162
	v_mov_b32_e32 v161, v164
	s_lshl_b32 s0, s2, 8
	s_add_i32 s0, s0, s35
	v_add_u32_e32 v140, s0, v160
	s_lshl_b32 s0, s24, 8
	s_or_b32 s0, s0, s36
	v_ashrrev_i32_e32 v141, 31, v140
	v_lshl_add_u32 v142, v161, 3, s0
	v_lshlrev_b64 v[144:145], 12, v[140:141]
	v_lshl_add_u64 v[144:145], s[62:63], 0, v[144:145]
	v_ashrrev_i32_e32 v143, 31, v142
	v_lshl_add_u64 v[148:149], v[142:143], 1, v[144:145]
	s_nop 0
	s_nop 0
	s_nop 0
	v_and_b32_e32 v153, 64, v170
	v_xor_b32_e32 v152, 16, v170
	v_add_u32_e32 v173, 64, v153
	v_cmp_lt_i32_e32 vcc, v152, v173
	s_waitcnt vmcnt(13)
	v_and_b32_e32 v153, 0xffff0000, v190
	v_cndmask_b32_e32 v152, v170, v152, vcc
	v_lshlrev_b32_e32 v172, 2, v152
	v_lshlrev_b32_e32 v152, 16, v190
	v_lshlrev_b32_e32 v144, 16, v191
	v_and_b32_e32 v145, 0xffff0000, v191
	v_lshlrev_b32_e32 v154, 16, v192
	v_and_b32_e32 v155, 0xffff0000, v192
	v_lshlrev_b32_e32 v158, 16, v194
	v_and_b32_e32 v159, 0xffff0000, v194
	v_lshlrev_b32_e32 v148, 16, v195
	v_and_b32_e32 v149, 0xffff0000, v195
	v_lshlrev_b32_e32 v156, 16, v193
	v_and_b32_e32 v157, 0xffff0000, v193
	v_lshlrev_b32_e32 v174, 16, v196
	v_and_b32_e32 v175, 0xffff0000, v196
	v_pk_add_f32 v[144:145], v[126:127], v[144:145]
	v_pk_add_f32 v[146:147], v[124:125], v[152:153]
	v_pk_add_f32 v[126:127], v[120:121], v[154:155]
	v_pk_add_f32 v[118:119], v[118:119], v[148:149]
	v_pk_add_f32 v[120:121], v[116:117], v[158:159]
	v_lshlrev_b32_e32 v150, 16, v197
	v_and_b32_e32 v151, 0xffff0000, v197
	v_pk_add_f32 v[116:117], v[112:113], v[174:175]
	v_mul_f32_e32 v112, v147, v147
	v_mul_f32_e32 v113, v145, v145
	v_mul_f32_e32 v148, v121, v121
	v_mul_f32_e32 v149, v119, v119
	v_pk_add_f32 v[124:125], v[122:123], v[156:157]
	v_pk_add_f32 v[114:115], v[114:115], v[150:151]
	v_mul_f32_e32 v122, v127, v127
	v_mul_f32_e32 v150, v117, v117
	v_fmac_f32_e32 v112, v146, v146
	v_fmac_f32_e32 v113, v144, v144
	v_fmac_f32_e32 v148, v120, v120
	v_fmac_f32_e32 v149, v118, v118
	v_mul_f32_e32 v123, v125, v125
	v_mul_f32_e32 v151, v115, v115
	v_fmac_f32_e32 v122, v126, v126
	v_fmac_f32_e32 v150, v116, v116
	v_add_f32_e32 v112, v112, v113
	v_add_f32_e32 v113, v148, v149
	v_fmac_f32_e32 v123, v124, v124
	v_fmac_f32_e32 v151, v114, v114
	v_add_f32_e32 v112, v122, v112
	v_add_f32_e32 v113, v150, v113
	v_add_f32_e32 v112, v123, v112
	v_add_f32_e32 v113, v151, v113
	v_add_f32_e32 v112, v112, v113
	ds_bpermute_b32 v113, v172, v112
	v_xor_b32_e32 v122, 32, v170
	v_cmp_lt_i32_e32 vcc, v122, v173
	s_nop 1
	v_cndmask_b32_e32 v122, v170, v122, vcc
	v_lshlrev_b32_e32 v173, 2, v122
	s_waitcnt lgkmcnt(0)
	v_add_f32_e32 v122, v112, v113
	ds_bpermute_b32 v123, v173, v122
	v_cmp_eq_u32_e32 vcc, 0, v161
	v_lshl_add_u64 v[112:113], v[140:141], 2, s[6:7]
	s_and_saveexec_b64 s[0:1], vcc
	s_cbranch_execz .LBB0_1454
	s_waitcnt lgkmcnt(0)
	v_add_f32_e32 v122, v122, v123
	global_atomic_add_f32 v[112:113], v122, off
.LBB0_1454:
	s_or_b64 exec, exec, s[0:1]
	v_add_u32_e32 v122, 16, v140
	s_waitcnt lgkmcnt(0)
	v_ashrrev_i32_e32 v123, 31, v122
	v_lshlrev_b64 v[148:149], 12, v[122:123]
	v_lshl_add_u64 v[148:149], s[62:63], 0, v[148:149]
	v_lshl_add_u64 v[152:153], v[142:143], 1, v[148:149]
	global_load_dwordx4 v[190:193], v255, s[62:63] offset:256
	s_nop 0
	s_nop 0
	s_waitcnt vmcnt(14)
	v_lshlrev_b32_e32 v156, 16, v198
	v_and_b32_e32 v157, 0xffff0000, v198
	v_lshlrev_b32_e32 v148, 16, v199
	v_and_b32_e32 v149, 0xffff0000, v199
	s_waitcnt vmcnt(13)
	v_lshlrev_b32_e32 v174, 16, v202
	v_and_b32_e32 v175, 0xffff0000, v202
	v_lshlrev_b32_e32 v152, 16, v203
	v_and_b32_e32 v153, 0xffff0000, v203
	v_lshlrev_b32_e32 v158, 16, v200
	v_and_b32_e32 v159, 0xffff0000, v200
	v_lshlrev_b32_e32 v176, 16, v204
	v_and_b32_e32 v177, 0xffff0000, v204
	v_pk_add_f32 v[110:111], v[110:111], v[148:149]
	v_pk_add_f32 v[148:149], v[108:109], v[156:157]
	v_pk_add_f32 v[102:103], v[102:103], v[152:153]
	v_pk_add_f32 v[100:101], v[100:101], v[174:175]
	v_lshlrev_b32_e32 v150, 16, v201
	v_and_b32_e32 v151, 0xffff0000, v201
	v_lshlrev_b32_e32 v154, 16, v205
	v_and_b32_e32 v155, 0xffff0000, v205
	v_pk_add_f32 v[108:109], v[104:105], v[158:159]
	v_pk_add_f32 v[96:97], v[96:97], v[176:177]
	v_mul_f32_e32 v104, v149, v149
	v_mul_f32_e32 v105, v111, v111
	v_mul_f32_e32 v152, v101, v101
	v_mul_f32_e32 v153, v103, v103
	v_pk_add_f32 v[106:107], v[106:107], v[150:151]
	v_pk_add_f32 v[98:99], v[98:99], v[154:155]
	v_mul_f32_e32 v150, v109, v109
	v_mul_f32_e32 v154, v97, v97
	v_fmac_f32_e32 v104, v148, v148
	v_fmac_f32_e32 v105, v110, v110
	v_fmac_f32_e32 v152, v100, v100
	v_fmac_f32_e32 v153, v102, v102
	v_mul_f32_e32 v151, v107, v107
	v_mul_f32_e32 v155, v99, v99
	v_fmac_f32_e32 v150, v108, v108
	v_fmac_f32_e32 v154, v96, v96
	v_add_f32_e32 v104, v104, v105
	v_add_f32_e32 v105, v152, v153
	v_fmac_f32_e32 v151, v106, v106
	v_fmac_f32_e32 v155, v98, v98
	v_add_f32_e32 v104, v150, v104
	v_add_f32_e32 v105, v154, v105
	v_add_f32_e32 v104, v151, v104
	v_add_f32_e32 v105, v155, v105
	v_add_f32_e32 v104, v104, v105
	ds_bpermute_b32 v105, v172, v104
	s_waitcnt lgkmcnt(0)
	v_add_f32_e32 v104, v104, v105
	ds_bpermute_b32 v105, v173, v104
	s_and_saveexec_b64 s[0:1], vcc
	s_cbranch_execz .LBB0_1456
	v_lshl_add_u64 v[150:151], v[122:123], 2, s[6:7]
	s_waitcnt lgkmcnt(0)
	v_add_f32_e32 v104, v104, v105
	global_atomic_add_f32 v[150:151], v104, off
.LBB0_1456:
	s_or_b64 exec, exec, s[0:1]
	v_add_u32_e32 v104, 32, v140
	s_waitcnt lgkmcnt(0)
	v_ashrrev_i32_e32 v105, 31, v104
	v_lshlrev_b64 v[150:151], 12, v[104:105]
	v_lshl_add_u64 v[150:151], s[62:63], 0, v[150:151]
	v_lshl_add_u64 v[154:155], v[142:143], 1, v[150:151]
	s_nop 0
	s_nop 0
	s_nop 0
	s_waitcnt vmcnt(13)
	v_lshlrev_b32_e32 v158, 16, v206
	v_and_b32_e32 v159, 0xffff0000, v206
	v_lshlrev_b32_e32 v150, 16, v207
	v_and_b32_e32 v151, 0xffff0000, v207
	s_waitcnt vmcnt(12)
	v_lshlrev_b32_e32 v176, 16, v210
	v_and_b32_e32 v177, 0xffff0000, v210
	v_lshlrev_b32_e32 v154, 16, v211
	v_and_b32_e32 v155, 0xffff0000, v211
	v_lshlrev_b32_e32 v174, 16, v208
	v_and_b32_e32 v175, 0xffff0000, v208
	v_lshlrev_b32_e32 v178, 16, v212
	v_and_b32_e32 v179, 0xffff0000, v212
	v_pk_add_f32 v[94:95], v[94:95], v[150:151]
	v_pk_add_f32 v[150:151], v[92:93], v[158:159]
	v_pk_add_f32 v[86:87], v[86:87], v[154:155]
	v_pk_add_f32 v[84:85], v[84:85], v[176:177]
	v_lshlrev_b32_e32 v152, 16, v209
	v_and_b32_e32 v153, 0xffff0000, v209
	v_lshlrev_b32_e32 v156, 16, v213
	v_and_b32_e32 v157, 0xffff0000, v213
	v_pk_add_f32 v[92:93], v[88:89], v[174:175]
	v_pk_add_f32 v[80:81], v[80:81], v[178:179]
	v_mul_f32_e32 v88, v151, v151
	v_mul_f32_e32 v89, v95, v95
	v_mul_f32_e32 v154, v85, v85
	v_mul_f32_e32 v155, v87, v87
	v_pk_add_f32 v[90:91], v[90:91], v[152:153]
	v_pk_add_f32 v[82:83], v[82:83], v[156:157]
	v_mul_f32_e32 v152, v93, v93
	v_mul_f32_e32 v156, v81, v81
	v_fmac_f32_e32 v88, v150, v150
	v_fmac_f32_e32 v89, v94, v94
	v_fmac_f32_e32 v154, v84, v84
	v_fmac_f32_e32 v155, v86, v86
	v_mul_f32_e32 v153, v91, v91
	v_mul_f32_e32 v157, v83, v83
	v_fmac_f32_e32 v152, v92, v92
	v_fmac_f32_e32 v156, v80, v80
	v_add_f32_e32 v88, v88, v89
	v_add_f32_e32 v89, v154, v155
	v_fmac_f32_e32 v153, v90, v90
	v_fmac_f32_e32 v157, v82, v82
	v_add_f32_e32 v88, v152, v88
	v_add_f32_e32 v89, v156, v89
	v_add_f32_e32 v88, v153, v88
	v_add_f32_e32 v89, v157, v89
	v_add_f32_e32 v88, v88, v89
	ds_bpermute_b32 v89, v172, v88
	s_waitcnt lgkmcnt(0)
	v_add_f32_e32 v88, v88, v89
	ds_bpermute_b32 v89, v173, v88
	s_and_saveexec_b64 s[0:1], vcc
	s_cbranch_execz .LBB0_1458
	v_lshl_add_u64 v[152:153], v[104:105], 2, s[6:7]
	s_waitcnt lgkmcnt(0)
	v_add_f32_e32 v88, v88, v89
	global_atomic_add_f32 v[152:153], v88, off
.LBB0_1458:
	s_or_b64 exec, exec, s[0:1]
	v_add_u32_e32 v88, 48, v140
	s_waitcnt lgkmcnt(0)
	v_ashrrev_i32_e32 v89, 31, v88
	v_lshlrev_b64 v[152:153], 12, v[88:89]
	v_lshl_add_u64 v[152:153], s[62:63], 0, v[152:153]
	v_lshl_add_u64 v[156:157], v[142:143], 1, v[152:153]
	s_nop 0
	s_nop 0
	s_nop 0
	s_waitcnt vmcnt(12)
	v_lshlrev_b32_e32 v174, 16, v214
	v_and_b32_e32 v175, 0xffff0000, v214
	v_lshlrev_b32_e32 v152, 16, v215
	v_and_b32_e32 v153, 0xffff0000, v215
	s_waitcnt vmcnt(11)
	v_lshlrev_b32_e32 v178, 16, v218
	v_and_b32_e32 v179, 0xffff0000, v218
	v_lshlrev_b32_e32 v156, 16, v219
	v_and_b32_e32 v157, 0xffff0000, v219
	v_lshlrev_b32_e32 v176, 16, v216
	v_and_b32_e32 v177, 0xffff0000, v216
	v_lshlrev_b32_e32 v180, 16, v220
	v_and_b32_e32 v181, 0xffff0000, v220
	v_pk_add_f32 v[78:79], v[78:79], v[152:153]
	v_pk_add_f32 v[152:153], v[76:77], v[174:175]
	v_pk_add_f32 v[70:71], v[70:71], v[156:157]
	v_pk_add_f32 v[68:69], v[68:69], v[178:179]
	v_lshlrev_b32_e32 v154, 16, v217
	v_and_b32_e32 v155, 0xffff0000, v217
	v_lshlrev_b32_e32 v158, 16, v221
	v_and_b32_e32 v159, 0xffff0000, v221
	v_pk_add_f32 v[76:77], v[72:73], v[176:177]
	v_pk_add_f32 v[64:65], v[64:65], v[180:181]
	v_mul_f32_e32 v72, v153, v153
	v_mul_f32_e32 v73, v79, v79
	v_mul_f32_e32 v156, v69, v69
	v_mul_f32_e32 v157, v71, v71
	v_pk_add_f32 v[74:75], v[74:75], v[154:155]
	v_pk_add_f32 v[66:67], v[66:67], v[158:159]
	v_mul_f32_e32 v154, v77, v77
	v_mul_f32_e32 v158, v65, v65
	v_fmac_f32_e32 v72, v152, v152
	v_fmac_f32_e32 v73, v78, v78
	v_fmac_f32_e32 v156, v68, v68
	v_fmac_f32_e32 v157, v70, v70
	v_mul_f32_e32 v155, v75, v75
	v_mul_f32_e32 v159, v67, v67
	v_fmac_f32_e32 v154, v76, v76
	v_fmac_f32_e32 v158, v64, v64
	v_add_f32_e32 v72, v72, v73
	v_add_f32_e32 v73, v156, v157
	v_fmac_f32_e32 v155, v74, v74
	v_fmac_f32_e32 v159, v66, v66
	v_add_f32_e32 v72, v154, v72
	v_add_f32_e32 v73, v158, v73
	v_add_f32_e32 v72, v155, v72
	v_add_f32_e32 v73, v159, v73
	v_add_f32_e32 v72, v72, v73
	ds_bpermute_b32 v73, v172, v72
	s_waitcnt lgkmcnt(0)
	v_add_f32_e32 v72, v72, v73
	ds_bpermute_b32 v73, v173, v72
	s_and_saveexec_b64 s[0:1], vcc
	s_cbranch_execz .LBB0_1460
	v_lshl_add_u64 v[154:155], v[88:89], 2, s[6:7]
	s_waitcnt lgkmcnt(0)
	v_add_f32_e32 v72, v72, v73
	global_atomic_add_f32 v[154:155], v72, off
.LBB0_1460:
	s_or_b64 exec, exec, s[0:1]
	v_add_u32_e32 v72, 0x80, v140
	s_waitcnt lgkmcnt(0)
	v_ashrrev_i32_e32 v73, 31, v72
	v_lshlrev_b64 v[154:155], 12, v[72:73]
	v_lshl_add_u64 v[154:155], s[62:63], 0, v[154:155]
	v_lshl_add_u64 v[158:159], v[142:143], 1, v[154:155]
	s_nop 0
	s_nop 0
	s_waitcnt vmcnt(11)
	v_lshlrev_b32_e32 v158, 16, v222
	v_and_b32_e32 v159, 0xffff0000, v222
	v_lshlrev_b32_e32 v154, 16, v223
	v_and_b32_e32 v155, 0xffff0000, v223
	s_waitcnt vmcnt(10)
	v_lshlrev_b32_e32 v180, 16, v230
	v_and_b32_e32 v181, 0xffff0000, v230
	v_lshlrev_b32_e32 v174, 16, v231
	v_and_b32_e32 v175, 0xffff0000, v231
	v_lshlrev_b32_e32 v178, 16, v224
	v_and_b32_e32 v179, 0xffff0000, v224
	v_lshlrev_b32_e32 v182, 16, v232
	v_and_b32_e32 v183, 0xffff0000, v232
	v_pk_add_f32 v[62:63], v[62:63], v[154:155]
	v_pk_add_f32 v[154:155], v[60:61], v[158:159]
	v_pk_add_f32 v[54:55], v[54:55], v[174:175]
	v_pk_add_f32 v[52:53], v[52:53], v[180:181]
	v_lshlrev_b32_e32 v156, 16, v225
	v_and_b32_e32 v157, 0xffff0000, v225
	v_lshlrev_b32_e32 v176, 16, v233
	v_and_b32_e32 v177, 0xffff0000, v233
	v_pk_add_f32 v[60:61], v[56:57], v[178:179]
	v_pk_add_f32 v[48:49], v[48:49], v[182:183]
	v_mul_f32_e32 v56, v155, v155
	v_mul_f32_e32 v57, v63, v63
	v_mul_f32_e32 v158, v53, v53
	v_mul_f32_e32 v159, v55, v55
	v_pk_add_f32 v[58:59], v[58:59], v[156:157]
	v_pk_add_f32 v[50:51], v[50:51], v[176:177]
	v_mul_f32_e32 v156, v61, v61
	v_mul_f32_e32 v174, v49, v49
	v_fmac_f32_e32 v56, v154, v154
	v_fmac_f32_e32 v57, v62, v62
	v_fmac_f32_e32 v158, v52, v52
	v_fmac_f32_e32 v159, v54, v54
	v_mul_f32_e32 v157, v59, v59
	v_mul_f32_e32 v175, v51, v51
	v_fmac_f32_e32 v156, v60, v60
	v_fmac_f32_e32 v174, v48, v48
	v_add_f32_e32 v56, v56, v57
	v_add_f32_e32 v57, v158, v159
	v_fmac_f32_e32 v157, v58, v58
	v_fmac_f32_e32 v175, v50, v50
	v_add_f32_e32 v56, v156, v56
	v_add_f32_e32 v57, v174, v57
	v_add_f32_e32 v56, v157, v56
	v_add_f32_e32 v57, v175, v57
	v_add_f32_e32 v56, v56, v57
	ds_bpermute_b32 v57, v172, v56
	s_waitcnt lgkmcnt(0)
	v_add_f32_e32 v56, v56, v57
	ds_bpermute_b32 v57, v173, v56
	s_and_saveexec_b64 s[0:1], vcc
	s_cbranch_execz .LBB0_1462
	v_lshl_add_u64 v[156:157], v[72:73], 2, s[6:7]
	s_waitcnt lgkmcnt(0)
	v_add_f32_e32 v56, v56, v57
	global_atomic_add_f32 v[156:157], v56, off
.LBB0_1462:
	s_or_b64 exec, exec, s[0:1]
	v_add_u32_e32 v56, 0x90, v140
	s_waitcnt lgkmcnt(0)
	v_ashrrev_i32_e32 v57, 31, v56
	v_lshlrev_b64 v[156:157], 12, v[56:57]
	v_lshl_add_u64 v[156:157], s[62:63], 0, v[156:157]
	v_lshl_add_u64 v[174:175], v[142:143], 1, v[156:157]
	s_nop 0
	s_nop 0
	s_nop 0
	s_waitcnt vmcnt(10)
	v_lshlrev_b32_e32 v178, 16, v234
	v_and_b32_e32 v179, 0xffff0000, v234
	v_lshlrev_b32_e32 v156, 16, v235
	v_and_b32_e32 v157, 0xffff0000, v235
	s_waitcnt vmcnt(9)
	v_lshlrev_b32_e32 v182, 16, v238
	v_and_b32_e32 v183, 0xffff0000, v238
	v_lshlrev_b32_e32 v174, 16, v239
	v_and_b32_e32 v175, 0xffff0000, v239
	v_lshlrev_b32_e32 v180, 16, v236
	v_and_b32_e32 v181, 0xffff0000, v236
	v_lshlrev_b32_e32 v184, 16, v240
	v_and_b32_e32 v185, 0xffff0000, v240
	v_pk_add_f32 v[46:47], v[46:47], v[156:157]
	v_pk_add_f32 v[156:157], v[44:45], v[178:179]
	v_pk_add_f32 v[38:39], v[38:39], v[174:175]
	v_pk_add_f32 v[36:37], v[36:37], v[182:183]
	v_lshlrev_b32_e32 v158, 16, v237
	v_and_b32_e32 v159, 0xffff0000, v237
	v_lshlrev_b32_e32 v176, 16, v241
	v_and_b32_e32 v177, 0xffff0000, v241
	v_pk_add_f32 v[44:45], v[40:41], v[180:181]
	v_pk_add_f32 v[32:33], v[32:33], v[184:185]
	v_mul_f32_e32 v40, v157, v157
	v_mul_f32_e32 v41, v47, v47
	v_mul_f32_e32 v174, v37, v37
	v_mul_f32_e32 v175, v39, v39
	v_pk_add_f32 v[42:43], v[42:43], v[158:159]
	v_pk_add_f32 v[34:35], v[34:35], v[176:177]
	v_mul_f32_e32 v158, v45, v45
	v_mul_f32_e32 v176, v33, v33
	v_fmac_f32_e32 v40, v156, v156
	v_fmac_f32_e32 v41, v46, v46
	v_fmac_f32_e32 v174, v36, v36
	v_fmac_f32_e32 v175, v38, v38
	v_mul_f32_e32 v159, v43, v43
	v_mul_f32_e32 v177, v35, v35
	v_fmac_f32_e32 v158, v44, v44
	v_fmac_f32_e32 v176, v32, v32
	v_add_f32_e32 v40, v40, v41
	v_add_f32_e32 v41, v174, v175
	v_fmac_f32_e32 v159, v42, v42
	v_fmac_f32_e32 v177, v34, v34
	v_add_f32_e32 v40, v158, v40
	v_add_f32_e32 v41, v176, v41
	v_add_f32_e32 v40, v159, v40
	v_add_f32_e32 v41, v177, v41
	v_add_f32_e32 v40, v40, v41
	ds_bpermute_b32 v41, v172, v40
	s_waitcnt lgkmcnt(0)
	v_add_f32_e32 v40, v40, v41
	ds_bpermute_b32 v41, v173, v40
	s_and_saveexec_b64 s[0:1], vcc
	s_cbranch_execz .LBB0_1464
	v_lshl_add_u64 v[158:159], v[56:57], 2, s[6:7]
	s_waitcnt lgkmcnt(0)
	v_add_f32_e32 v40, v40, v41
	global_atomic_add_f32 v[158:159], v40, off
.LBB0_1464:
	s_or_b64 exec, exec, s[0:1]
	v_add_u32_e32 v40, 0xa0, v140
	s_waitcnt lgkmcnt(0)
	v_ashrrev_i32_e32 v41, 31, v40
	v_lshlrev_b64 v[158:159], 12, v[40:41]
	v_lshl_add_u64 v[158:159], s[62:63], 0, v[158:159]
	v_lshl_add_u64 v[158:159], v[142:143], 1, v[158:159]
	s_nop 0
	s_nop 0
	s_waitcnt vmcnt(9)
	v_lshlrev_b32_e32 v158, 16, v242
	v_and_b32_e32 v159, 0xffff0000, v242
	v_lshlrev_b32_e32 v174, 16, v243
	v_and_b32_e32 v175, 0xffff0000, v243
	s_waitcnt vmcnt(8)
	v_lshlrev_b32_e32 v184, 16, v246
	v_and_b32_e32 v185, 0xffff0000, v246
	v_lshlrev_b32_e32 v178, 16, v247
	v_and_b32_e32 v179, 0xffff0000, v247
	v_lshlrev_b32_e32 v182, 16, v244
	v_and_b32_e32 v183, 0xffff0000, v244
	v_lshlrev_b32_e32 v176, 16, v245
	v_and_b32_e32 v177, 0xffff0000, v245
	v_lshlrev_b32_e32 v186, 16, v248
	v_and_b32_e32 v187, 0xffff0000, v248
	v_pk_add_f32 v[30:31], v[30:31], v[174:175]
	v_pk_add_f32 v[158:159], v[28:29], v[158:159]
	v_pk_add_f32 v[22:23], v[22:23], v[178:179]
	v_pk_add_f32 v[20:21], v[20:21], v[184:185]
	v_lshlrev_b32_e32 v180, 16, v249
	v_and_b32_e32 v181, 0xffff0000, v249
	v_pk_add_f32 v[26:27], v[26:27], v[176:177]
	v_pk_add_f32 v[28:29], v[24:25], v[182:183]
	v_pk_add_f32 v[16:17], v[16:17], v[186:187]
	v_mul_f32_e32 v24, v159, v159
	v_mul_f32_e32 v25, v31, v31
	v_mul_f32_e32 v176, v21, v21
	v_mul_f32_e32 v177, v23, v23
	v_pk_add_f32 v[18:19], v[18:19], v[180:181]
	v_mul_f32_e32 v174, v29, v29
	v_mul_f32_e32 v178, v17, v17
	v_fmac_f32_e32 v24, v158, v158
	v_fmac_f32_e32 v25, v30, v30
	v_fmac_f32_e32 v176, v20, v20
	v_fmac_f32_e32 v177, v22, v22
	v_mul_f32_e32 v175, v27, v27
	v_mul_f32_e32 v179, v19, v19
	v_fmac_f32_e32 v174, v28, v28
	v_fmac_f32_e32 v178, v16, v16
	v_add_f32_e32 v24, v24, v25
	v_add_f32_e32 v25, v176, v177
	v_fmac_f32_e32 v175, v26, v26
	v_fmac_f32_e32 v179, v18, v18
	v_add_f32_e32 v24, v174, v24
	v_add_f32_e32 v25, v178, v25
	v_add_f32_e32 v24, v175, v24
	v_add_f32_e32 v25, v179, v25
	v_add_f32_e32 v24, v24, v25
	ds_bpermute_b32 v25, v172, v24
	s_waitcnt lgkmcnt(0)
	v_add_f32_e32 v24, v24, v25
	ds_bpermute_b32 v25, v173, v24
	s_and_saveexec_b64 s[0:1], vcc
	s_cbranch_execz .LBB0_1466
	v_lshl_add_u64 v[174:175], v[40:41], 2, s[6:7]
	s_waitcnt lgkmcnt(0)
	v_add_f32_e32 v24, v24, v25
	global_atomic_add_f32 v[174:175], v24, off
.LBB0_1466:
	s_or_b64 exec, exec, s[0:1]
	v_add_u32_e32 v24, 0xb0, v140
	s_waitcnt lgkmcnt(0)
	v_ashrrev_i32_e32 v25, 31, v24
	v_lshlrev_b64 v[174:175], 12, v[24:25]
	v_lshl_add_u64 v[174:175], s[62:63], 0, v[174:175]
	v_lshl_add_u64 v[178:179], v[142:143], 1, v[174:175]
	s_nop 0
	s_nop 0
	s_nop 0
	s_waitcnt vmcnt(8)
	v_lshlrev_b32_e32 v182, 16, v250
	v_and_b32_e32 v183, 0xffff0000, v250
	v_lshlrev_b32_e32 v174, 16, v251
	v_and_b32_e32 v175, 0xffff0000, v251
	s_waitcnt vmcnt(6)
	v_lshlrev_b32_e32 v186, 16, v190
	v_and_b32_e32 v187, 0xffff0000, v190
	v_lshlrev_b32_e32 v178, 16, v191
	v_and_b32_e32 v179, 0xffff0000, v191
	v_lshlrev_b32_e32 v184, 16, v252
	v_and_b32_e32 v185, 0xffff0000, v252
	v_lshlrev_b32_e32 v188, 16, v192
	v_and_b32_e32 v189, 0xffff0000, v192
	v_pk_add_f32 v[14:15], v[14:15], v[174:175]
	v_pk_add_f32 v[12:13], v[12:13], v[182:183]
	v_pk_add_f32 v[6:7], v[6:7], v[178:179]
	v_pk_add_f32 v[4:5], v[4:5], v[186:187]
	v_lshlrev_b32_e32 v176, 16, v253
	v_and_b32_e32 v177, 0xffff0000, v253
	v_lshlrev_b32_e32 v180, 16, v193
	v_and_b32_e32 v181, 0xffff0000, v193
	v_pk_add_f32 v[8:9], v[8:9], v[184:185]
	v_pk_add_f32 v[0:1], v[0:1], v[188:189]
	v_mul_f32_e32 v174, v13, v13
	v_mul_f32_e32 v175, v15, v15
	v_mul_f32_e32 v178, v5, v5
	v_mul_f32_e32 v179, v7, v7
	v_pk_add_f32 v[10:11], v[10:11], v[176:177]
	v_pk_add_f32 v[2:3], v[2:3], v[180:181]
	v_mul_f32_e32 v176, v9, v9
	v_mul_f32_e32 v180, v1, v1
	v_fmac_f32_e32 v174, v12, v12
	v_fmac_f32_e32 v175, v14, v14
	v_fmac_f32_e32 v178, v4, v4
	v_fmac_f32_e32 v179, v6, v6
	v_mul_f32_e32 v177, v11, v11
	v_mul_f32_e32 v181, v3, v3
	v_fmac_f32_e32 v176, v8, v8
	v_fmac_f32_e32 v180, v0, v0
	v_add_f32_e32 v174, v174, v175
	v_add_f32_e32 v175, v178, v179
	v_fmac_f32_e32 v177, v10, v10
	v_fmac_f32_e32 v181, v2, v2
	v_add_f32_e32 v174, v176, v174
	v_add_f32_e32 v175, v180, v175
	v_add_f32_e32 v174, v177, v174
	v_add_f32_e32 v175, v181, v175
	v_add_f32_e32 v174, v174, v175
	ds_bpermute_b32 v172, v172, v174
	s_waitcnt lgkmcnt(0)
	v_add_f32_e32 v172, v174, v172
	ds_bpermute_b32 v173, v173, v172
	s_and_saveexec_b64 s[0:1], vcc
	s_cbranch_execz .LBB0_1468
	v_lshl_add_u64 v[174:175], v[24:25], 2, s[6:7]
	s_waitcnt lgkmcnt(0)
	v_add_f32_e32 v172, v172, v173
	global_atomic_add_f32 v[174:175], v172, off

.LBB0_1477:
	s_nop 1
	v_lshlrev_b64 v[160:161], 2, v[142:143]
	v_lshl_add_u64 v[142:143], s[80:81], 0, v[160:161]
	global_load_dword v190, v[112:113], off sc1
	global_load_dword v191, v[112:113], off offset:64 sc1
	global_load_dword v192, v[112:113], off offset:128 sc1
	global_load_dword v193, v[112:113], off offset:192 sc1
	global_load_dword v194, v[112:113], off offset:512 sc1
	global_load_dword v195, v[112:113], off offset:576 sc1
	global_load_dword v196, v[112:113], off offset:640 sc1
	global_load_dword v197, v[112:113], off offset:704 sc1
	global_load_dwordx4 v[198:201], v[142:143], off
	global_load_dwordx4 v[202:205], v[142:143], off offset:16
	global_load_dwordx4 v[206:209], v[142:143], off offset:512
	global_load_dwordx4 v[210:213], v[142:143], off offset:528
	s_waitcnt lgkmcnt(0)
	s_nop 1
	s_nop 1
	v_lshlrev_b64 v[140:141], 13, v[140:141]
	v_lshl_add_u64 v[140:141], s[82:83], 0, v[140:141]
	v_lshl_add_u64 v[140:141], v[140:141], 0, v[160:161]
	v_lshlrev_b64 v[122:123], 13, v[122:123]
	v_lshl_add_u64 v[122:123], s[82:83], 0, v[122:123]
	v_lshl_add_u64 v[122:123], v[122:123], 0, v[160:161]
	v_lshlrev_b64 v[104:105], 13, v[104:105]
	v_lshl_add_u64 v[104:105], s[82:83], 0, v[104:105]
	v_lshl_add_u64 v[104:105], v[104:105], 0, v[160:161]
	v_lshlrev_b64 v[88:89], 13, v[88:89]
	v_lshl_add_u64 v[88:89], s[82:83], 0, v[88:89]
	v_lshl_add_u64 v[88:89], v[88:89], 0, v[160:161]
	v_lshlrev_b64 v[72:73], 13, v[72:73]
	v_lshl_add_u64 v[72:73], s[82:83], 0, v[72:73]
	v_lshl_add_u64 v[72:73], v[72:73], 0, v[160:161]
	v_lshlrev_b64 v[56:57], 13, v[56:57]
	v_lshl_add_u64 v[56:57], s[82:83], 0, v[56:57]
	v_lshl_add_u64 v[56:57], v[56:57], 0, v[160:161]
	v_lshlrev_b64 v[40:41], 13, v[40:41]
	v_lshl_add_u64 v[40:41], s[82:83], 0, v[40:41]
	v_lshl_add_u64 v[40:41], v[40:41], 0, v[160:161]
	v_lshlrev_b64 v[24:25], 13, v[24:25]
	v_lshl_add_u64 v[24:25], s[82:83], 0, v[24:25]
	v_lshl_add_u64 v[24:25], v[24:25], 0, v[160:161]
	s_mov_b64 s[0:1], -1
	s_waitcnt vmcnt(11)
	v_fmamk_f32 v180, v190, 0x3a000000, v171
	v_mul_f32_e32 v181, 0x4b800000, v180
	v_cmp_gt_f32_e32 vcc, s44, v180
	s_nop 1
	v_cndmask_b32_e32 v180, v180, v181, vcc
	v_rsq_f32_e32 v180, v180
	s_nop 0
	v_mul_f32_e32 v181, 0x45800000, v180
	v_cndmask_b32_e32 v180, v180, v181, vcc
	v_pk_mul_f32 v[146:147], v[146:147], v[180:181] op_sel_hi:[1,0]
	v_pk_mul_f32 v[144:145], v[144:145], v[180:181] op_sel_hi:[1,0]
	v_pk_mul_f32 v[182:183], v[126:127], v[180:181] op_sel_hi:[1,0]
	v_pk_mul_f32 v[184:185], v[124:125], v[180:181] op_sel_hi:[1,0]
	s_waitcnt vmcnt(3)
	v_pk_mul_f32 v[126:127], v[200:201], v[144:145]
	v_pk_mul_f32 v[124:125], v[198:199], v[146:147]
	s_waitcnt vmcnt(2)
	v_pk_mul_f32 v[146:147], v[204:205], v[184:185]
	v_pk_mul_f32 v[144:145], v[202:203], v[182:183]
	global_store_dwordx4 v[140:141], v[124:127], off
	global_store_dwordx4 v[140:141], v[144:147], off offset:16
	s_nop 1
	s_nop 0
	s_nop 1
	v_pk_mul_f32 v[118:119], v[118:119], v[180:181] op_sel_hi:[1,0]
	v_pk_mul_f32 v[120:121], v[120:121], v[180:181] op_sel_hi:[1,0]
	v_pk_mul_f32 v[172:173], v[114:115], v[180:181] op_sel_hi:[1,0]
	v_pk_mul_f32 v[174:175], v[116:117], v[180:181] op_sel_hi:[1,0]
	s_waitcnt vmcnt(3)
	v_pk_mul_f32 v[114:115], v[206:207], v[120:121]
	v_pk_mul_f32 v[116:117], v[208:209], v[118:119]
	s_waitcnt vmcnt(2)
	v_pk_mul_f32 v[118:119], v[210:211], v[174:175]
	v_pk_mul_f32 v[120:121], v[212:213], v[172:173]
	global_store_dwordx4 v[140:141], v[114:117], off offset:512
	global_store_dwordx4 v[140:141], v[118:121], off offset:528
	s_nop 1
	s_nop 0
	s_nop 1
	s_nop 1
	s_nop 0
	v_fmamk_f32 v124, v191, 0x3a000000, v171
	v_mul_f32_e32 v125, 0x4b800000, v124
	v_cmp_gt_f32_e32 vcc, s44, v124
	s_nop 1
	v_cndmask_b32_e32 v124, v124, v125, vcc
	v_rsq_f32_e32 v124, v124
	s_nop 0
	v_mul_f32_e32 v125, 0x45800000, v124
	v_cndmask_b32_e32 v124, v124, v125, vcc
	v_pk_mul_f32 v[126:127], v[148:149], v[124:125] op_sel_hi:[1,0]
	v_pk_mul_f32 v[110:111], v[110:111], v[124:125] op_sel_hi:[1,0]
	v_pk_mul_f32 v[140:141], v[108:109], v[124:125] op_sel_hi:[1,0]
	v_pk_mul_f32 v[144:145], v[106:107], v[124:125] op_sel_hi:[1,0]
	s_nop 0
	v_pk_mul_f32 v[108:109], v[200:201], v[110:111]
	v_pk_mul_f32 v[106:107], v[198:199], v[126:127]
	s_nop 0
	v_pk_mul_f32 v[116:117], v[204:205], v[144:145]
	v_pk_mul_f32 v[114:115], v[202:203], v[140:141]
	global_store_dwordx4 v[122:123], v[106:109], off
	global_store_dwordx4 v[122:123], v[114:117], off offset:16
	s_nop 1
	s_nop 0
	s_nop 1
	v_pk_mul_f32 v[102:103], v[102:103], v[124:125] op_sel_hi:[1,0]
	v_pk_mul_f32 v[100:101], v[100:101], v[124:125] op_sel_hi:[1,0]
	v_pk_mul_f32 v[110:111], v[98:99], v[124:125] op_sel_hi:[1,0]
	v_pk_mul_f32 v[118:119], v[96:97], v[124:125] op_sel_hi:[1,0]
	s_nop 0
	v_pk_mul_f32 v[96:97], v[206:207], v[100:101]
	v_pk_mul_f32 v[98:99], v[208:209], v[102:103]
	s_nop 0
	v_pk_mul_f32 v[100:101], v[210:211], v[118:119]
	v_pk_mul_f32 v[102:103], v[212:213], v[110:111]
	global_store_dwordx4 v[122:123], v[96:99], off offset:512
	global_store_dwordx4 v[122:123], v[100:103], off offset:528
	s_nop 1
	s_nop 0
	s_nop 1
	s_nop 1
	s_nop 0
	v_fmamk_f32 v106, v192, 0x3a000000, v171
	v_mul_f32_e32 v107, 0x4b800000, v106
	v_cmp_gt_f32_e32 vcc, s44, v106
	s_nop 1
	v_cndmask_b32_e32 v106, v106, v107, vcc
	v_rsq_f32_e32 v106, v106
	s_nop 0
	v_mul_f32_e32 v107, 0x45800000, v106
	v_cndmask_b32_e32 v106, v106, v107, vcc
	v_pk_mul_f32 v[108:109], v[150:151], v[106:107] op_sel_hi:[1,0]
	v_pk_mul_f32 v[94:95], v[94:95], v[106:107] op_sel_hi:[1,0]
	v_pk_mul_f32 v[110:111], v[92:93], v[106:107] op_sel_hi:[1,0]
	v_pk_mul_f32 v[114:115], v[90:91], v[106:107] op_sel_hi:[1,0]
	s_nop 0
	v_pk_mul_f32 v[92:93], v[200:201], v[94:95]
	v_pk_mul_f32 v[90:91], v[198:199], v[108:109]
	s_nop 0
	v_pk_mul_f32 v[96:97], v[204:205], v[114:115]
	v_pk_mul_f32 v[94:95], v[202:203], v[110:111]
	global_store_dwordx4 v[104:105], v[90:93], off
	global_store_dwordx4 v[104:105], v[94:97], off offset:16
	s_nop 1
	s_nop 0
	s_nop 1
	v_pk_mul_f32 v[86:87], v[86:87], v[106:107] op_sel_hi:[1,0]
	v_pk_mul_f32 v[84:85], v[84:85], v[106:107] op_sel_hi:[1,0]
	v_pk_mul_f32 v[98:99], v[82:83], v[106:107] op_sel_hi:[1,0]
	v_pk_mul_f32 v[100:101], v[80:81], v[106:107] op_sel_hi:[1,0]
	s_nop 0
	v_pk_mul_f32 v[80:81], v[206:207], v[84:85]
	v_pk_mul_f32 v[82:83], v[208:209], v[86:87]
	s_nop 0
	v_pk_mul_f32 v[84:85], v[210:211], v[100:101]
	v_pk_mul_f32 v[86:87], v[212:213], v[98:99]
	global_store_dwordx4 v[104:105], v[80:83], off offset:512
	global_store_dwordx4 v[104:105], v[84:87], off offset:528
	s_nop 1
	s_nop 0
	s_nop 1
	s_nop 1
	s_nop 0
	v_fmamk_f32 v90, v193, 0x3a000000, v171
	v_mul_f32_e32 v91, 0x4b800000, v90
	v_cmp_gt_f32_e32 vcc, s44, v90
	s_nop 1
	v_cndmask_b32_e32 v90, v90, v91, vcc
	v_rsq_f32_e32 v90, v90
	s_nop 0
	v_mul_f32_e32 v91, 0x45800000, v90
	v_cndmask_b32_e32 v90, v90, v91, vcc
	v_pk_mul_f32 v[92:93], v[152:153], v[90:91] op_sel_hi:[1,0]
	v_pk_mul_f32 v[78:79], v[78:79], v[90:91] op_sel_hi:[1,0]
	v_pk_mul_f32 v[94:95], v[76:77], v[90:91] op_sel_hi:[1,0]
	v_pk_mul_f32 v[96:97], v[74:75], v[90:91] op_sel_hi:[1,0]
	s_nop 0
	v_pk_mul_f32 v[76:77], v[200:201], v[78:79]
	v_pk_mul_f32 v[74:75], v[198:199], v[92:93]
	s_nop 0
	v_pk_mul_f32 v[80:81], v[204:205], v[96:97]
	v_pk_mul_f32 v[78:79], v[202:203], v[94:95]
	global_store_dwordx4 v[88:89], v[74:77], off
	global_store_dwordx4 v[88:89], v[78:81], off offset:16
	s_nop 1
	s_nop 0
	s_nop 1
	v_pk_mul_f32 v[70:71], v[70:71], v[90:91] op_sel_hi:[1,0]
	v_pk_mul_f32 v[68:69], v[68:69], v[90:91] op_sel_hi:[1,0]
	v_pk_mul_f32 v[82:83], v[66:67], v[90:91] op_sel_hi:[1,0]
	v_pk_mul_f32 v[84:85], v[64:65], v[90:91] op_sel_hi:[1,0]
	s_nop 0
	v_pk_mul_f32 v[64:65], v[206:207], v[68:69]
	v_pk_mul_f32 v[66:67], v[208:209], v[70:71]
	s_nop 0
	v_pk_mul_f32 v[68:69], v[210:211], v[84:85]
	v_pk_mul_f32 v[70:71], v[212:213], v[82:83]
	global_store_dwordx4 v[88:89], v[64:67], off offset:512
	global_store_dwordx4 v[88:89], v[68:71], off offset:528
	s_nop 1
	s_nop 0
	s_nop 1
	s_nop 1
	s_nop 0
	v_fmamk_f32 v74, v194, 0x3a000000, v171
	v_mul_f32_e32 v75, 0x4b800000, v74
	v_cmp_gt_f32_e32 vcc, s44, v74
	s_nop 1
	v_cndmask_b32_e32 v74, v74, v75, vcc
	v_rsq_f32_e32 v74, v74
	s_nop 0
	v_mul_f32_e32 v75, 0x45800000, v74
	v_cndmask_b32_e32 v74, v74, v75, vcc
	v_pk_mul_f32 v[76:77], v[154:155], v[74:75] op_sel_hi:[1,0]
	v_pk_mul_f32 v[62:63], v[62:63], v[74:75] op_sel_hi:[1,0]
	v_pk_mul_f32 v[78:79], v[60:61], v[74:75] op_sel_hi:[1,0]
	v_pk_mul_f32 v[80:81], v[58:59], v[74:75] op_sel_hi:[1,0]
	s_nop 0
	v_pk_mul_f32 v[60:61], v[200:201], v[62:63]
	v_pk_mul_f32 v[58:59], v[198:199], v[76:77]
	s_nop 0
	v_pk_mul_f32 v[64:65], v[204:205], v[80:81]
	v_pk_mul_f32 v[62:63], v[202:203], v[78:79]
	global_store_dwordx4 v[72:73], v[58:61], off
	global_store_dwordx4 v[72:73], v[62:65], off offset:16
	s_nop 1
	s_nop 0
	s_nop 1
	v_pk_mul_f32 v[54:55], v[54:55], v[74:75] op_sel_hi:[1,0]
	v_pk_mul_f32 v[52:53], v[52:53], v[74:75] op_sel_hi:[1,0]
	v_pk_mul_f32 v[66:67], v[50:51], v[74:75] op_sel_hi:[1,0]
	v_pk_mul_f32 v[68:69], v[48:49], v[74:75] op_sel_hi:[1,0]
	s_nop 0
	v_pk_mul_f32 v[48:49], v[206:207], v[52:53]
	v_pk_mul_f32 v[50:51], v[208:209], v[54:55]
	s_nop 0
	v_pk_mul_f32 v[52:53], v[210:211], v[68:69]
	v_pk_mul_f32 v[54:55], v[212:213], v[66:67]
	global_store_dwordx4 v[72:73], v[48:51], off offset:512
	global_store_dwordx4 v[72:73], v[52:55], off offset:528
	s_nop 1
	s_nop 0
	s_nop 1
	s_nop 1
	s_nop 0
	v_fmamk_f32 v58, v195, 0x3a000000, v171
	v_mul_f32_e32 v59, 0x4b800000, v58
	v_cmp_gt_f32_e32 vcc, s44, v58
	s_nop 1
	v_cndmask_b32_e32 v58, v58, v59, vcc
	v_rsq_f32_e32 v58, v58
	s_nop 0
	v_mul_f32_e32 v59, 0x45800000, v58
	v_cndmask_b32_e32 v58, v58, v59, vcc
	v_pk_mul_f32 v[60:61], v[156:157], v[58:59] op_sel_hi:[1,0]
	v_pk_mul_f32 v[46:47], v[46:47], v[58:59] op_sel_hi:[1,0]
	v_pk_mul_f32 v[62:63], v[44:45], v[58:59] op_sel_hi:[1,0]
	v_pk_mul_f32 v[64:65], v[42:43], v[58:59] op_sel_hi:[1,0]
	s_nop 0
	v_pk_mul_f32 v[44:45], v[200:201], v[46:47]
	v_pk_mul_f32 v[42:43], v[198:199], v[60:61]
	s_nop 0
	v_pk_mul_f32 v[48:49], v[204:205], v[64:65]
	v_pk_mul_f32 v[46:47], v[202:203], v[62:63]
	global_store_dwordx4 v[56:57], v[42:45], off
	global_store_dwordx4 v[56:57], v[46:49], off offset:16
	s_nop 1
	s_nop 0
	s_nop 1
	v_pk_mul_f32 v[38:39], v[38:39], v[58:59] op_sel_hi:[1,0]
	v_pk_mul_f32 v[36:37], v[36:37], v[58:59] op_sel_hi:[1,0]
	v_pk_mul_f32 v[50:51], v[34:35], v[58:59] op_sel_hi:[1,0]
	v_pk_mul_f32 v[52:53], v[32:33], v[58:59] op_sel_hi:[1,0]
	s_nop 0
	v_pk_mul_f32 v[32:33], v[206:207], v[36:37]
	v_pk_mul_f32 v[34:35], v[208:209], v[38:39]
	s_nop 0
	v_pk_mul_f32 v[36:37], v[210:211], v[52:53]
	v_pk_mul_f32 v[38:39], v[212:213], v[50:51]
	global_store_dwordx4 v[56:57], v[32:35], off offset:512
	global_store_dwordx4 v[56:57], v[36:39], off offset:528
	s_nop 1
	s_nop 0
	s_nop 1
	s_nop 1
	s_nop 0
	v_fmamk_f32 v42, v196, 0x3a000000, v171
	v_mul_f32_e32 v43, 0x4b800000, v42
	v_cmp_gt_f32_e32 vcc, s44, v42
	s_nop 1
	v_cndmask_b32_e32 v42, v42, v43, vcc
	v_rsq_f32_e32 v42, v42
	s_nop 0
	v_mul_f32_e32 v43, 0x45800000, v42
	v_cndmask_b32_e32 v42, v42, v43, vcc
	v_pk_mul_f32 v[44:45], v[158:159], v[42:43] op_sel_hi:[1,0]
	v_pk_mul_f32 v[30:31], v[30:31], v[42:43] op_sel_hi:[1,0]
	v_pk_mul_f32 v[46:47], v[28:29], v[42:43] op_sel_hi:[1,0]
	v_pk_mul_f32 v[48:49], v[26:27], v[42:43] op_sel_hi:[1,0]
	s_nop 0
	v_pk_mul_f32 v[28:29], v[200:201], v[30:31]
	v_pk_mul_f32 v[26:27], v[198:199], v[44:45]
	s_nop 0
	v_pk_mul_f32 v[32:33], v[204:205], v[48:49]
	v_pk_mul_f32 v[30:31], v[202:203], v[46:47]
	global_store_dwordx4 v[40:41], v[26:29], off
	global_store_dwordx4 v[40:41], v[30:33], off offset:16
	s_nop 1
	s_nop 0
	s_nop 1
	v_pk_mul_f32 v[22:23], v[22:23], v[42:43] op_sel_hi:[1,0]
	v_pk_mul_f32 v[20:21], v[20:21], v[42:43] op_sel_hi:[1,0]
	v_pk_mul_f32 v[34:35], v[18:19], v[42:43] op_sel_hi:[1,0]
	v_pk_mul_f32 v[36:37], v[16:17], v[42:43] op_sel_hi:[1,0]
	s_nop 0
	v_pk_mul_f32 v[16:17], v[206:207], v[20:21]
	v_pk_mul_f32 v[18:19], v[208:209], v[22:23]
	s_nop 0
	v_pk_mul_f32 v[20:21], v[210:211], v[36:37]
	v_pk_mul_f32 v[22:23], v[212:213], v[34:35]
	global_store_dwordx4 v[40:41], v[16:19], off offset:512
	global_store_dwordx4 v[40:41], v[20:23], off offset:528
	s_nop 1
	s_nop 0
	s_nop 1
	s_nop 1
	s_nop 0
	v_fmamk_f32 v26, v197, 0x3a000000, v171
	v_mul_f32_e32 v27, 0x4b800000, v26
	v_cmp_gt_f32_e32 vcc, s44, v26
	s_nop 1
	v_cndmask_b32_e32 v26, v26, v27, vcc
	v_rsq_f32_e32 v26, v26
	s_nop 0
	v_mul_f32_e32 v27, 0x45800000, v26
	v_cndmask_b32_e32 v26, v26, v27, vcc
	v_pk_mul_f32 v[12:13], v[12:13], v[26:27] op_sel_hi:[1,0]
	v_pk_mul_f32 v[14:15], v[14:15], v[26:27] op_sel_hi:[1,0]
	v_pk_mul_f32 v[28:29], v[8:9], v[26:27] op_sel_hi:[1,0]
	v_pk_mul_f32 v[30:31], v[10:11], v[26:27] op_sel_hi:[1,0]
	s_nop 0
	v_pk_mul_f32 v[10:11], v[200:201], v[14:15]
	v_pk_mul_f32 v[8:9], v[198:199], v[12:13]
	s_nop 0
	v_pk_mul_f32 v[14:15], v[204:205], v[30:31]
	v_pk_mul_f32 v[12:13], v[202:203], v[28:29]
	global_store_dwordx4 v[24:25], v[8:11], off
	global_store_dwordx4 v[24:25], v[12:15], off offset:16
	s_nop 1
	s_nop 0
	s_nop 1
	v_pk_mul_f32 v[6:7], v[6:7], v[26:27] op_sel_hi:[1,0]
	v_pk_mul_f32 v[4:5], v[4:5], v[26:27] op_sel_hi:[1,0]
	s_andn2_b64 vcc, exec, s[18:19]
	v_pk_mul_f32 v[16:17], v[2:3], v[26:27] op_sel_hi:[1,0]
	v_pk_mul_f32 v[18:19], v[0:1], v[26:27] op_sel_hi:[1,0]
	s_nop 0
	v_pk_mul_f32 v[0:1], v[206:207], v[4:5]
	v_pk_mul_f32 v[2:3], v[208:209], v[6:7]
	s_nop 0
	v_pk_mul_f32 v[4:5], v[210:211], v[18:19]
	v_pk_mul_f32 v[6:7], v[212:213], v[16:17]
	global_store_dwordx4 v[24:25], v[0:3], off offset:512
	global_store_dwordx4 v[24:25], v[4:7], off offset:528
	s_cbranch_vccnz .LBB0_1433
	s_andn2_b64 vcc, exec, s[4:5]
	s_cbranch_vccnz .LBB0_1432
	s_barrier
	s_branch .LBB0_1432
